# v51: up_kv k_nope epilogue rewritten by hand (pipelined rs reads, packed cvt, running offsets)
# baseline (speedup 1.0000x reference)
.LBB0_3143:
	s_waitcnt vmcnt(0)
	v_lshl_or_b32 v137, v129, 2, v130
	v_lshl_add_u32 v138, v137, 2, v214
	ds_read_b128 v[140:143], v138
	ds_read_b128 v[144:147], v138 offset:32
	ds_read_b128 v[148:151], v138 offset:64
	ds_read_b128 v[152:155], v138 offset:96
	ds_read_b128 v[156:159], v138 offset:128
	ds_read_b128 v[160:163], v138 offset:160
	ds_read_b128 v[164:167], v138 offset:192
	ds_read_b128 v[168:171], v138 offset:224
	v_add_u32_e32 v139, s78, v137
	v_lshlrev_b32_e32 v139, 10, v139
	v_lshl_add_u32 v188, v128, 1, v139
	s_waitcnt lgkmcnt(7)
	v_mul_f32_e32 v172, v112, v140
	v_mul_f32_e32 v173, v113, v141
	v_mul_f32_e32 v174, v114, v142
	v_mul_f32_e32 v175, v115, v143
	v_mul_f32_e32 v176, v48, v140
	v_mul_f32_e32 v177, v49, v141
	v_mul_f32_e32 v178, v50, v142
	v_mul_f32_e32 v179, v51, v143
	ds_read_b128 v[140:143], v138 offset:256
	v_cvt_pk_bf16_f32 v180, v172, v173
	v_cvt_pk_bf16_f32 v181, v174, v175
	v_cvt_pk_bf16_f32 v182, v176, v177
	v_cvt_pk_bf16_f32 v183, v178, v179
	global_store_short v188, v180, s[36:37]
	global_store_short v188, v182, s[36:37] offset:64
	v_add_u32_e32 v188, 0x400, v188
	global_store_short_d16_hi v188, v180, s[36:37]
	global_store_short_d16_hi v188, v182, s[36:37] offset:64
	v_add_u32_e32 v188, 0x400, v188
	global_store_short v188, v181, s[36:37]
	global_store_short v188, v183, s[36:37] offset:64
	v_add_u32_e32 v188, 0x400, v188
	global_store_short_d16_hi v188, v181, s[36:37]
	global_store_short_d16_hi v188, v183, s[36:37] offset:64
	v_add_u32_e32 v188, 0x1400, v188
	s_waitcnt lgkmcnt(7)
	v_mul_f32_e32 v172, v116, v144
	v_mul_f32_e32 v173, v117, v145
	v_mul_f32_e32 v174, v118, v146
	v_mul_f32_e32 v175, v119, v147
	v_mul_f32_e32 v176, v52, v144
	v_mul_f32_e32 v177, v53, v145
	v_mul_f32_e32 v178, v54, v146
	v_mul_f32_e32 v179, v55, v147
	ds_read_b128 v[144:147], v138 offset:288
	v_cvt_pk_bf16_f32 v184, v172, v173
	v_cvt_pk_bf16_f32 v185, v174, v175
	v_cvt_pk_bf16_f32 v186, v176, v177
	v_cvt_pk_bf16_f32 v187, v178, v179
	global_store_short v188, v184, s[36:37]
	global_store_short v188, v186, s[36:37] offset:64
	v_add_u32_e32 v188, 0x400, v188
	global_store_short_d16_hi v188, v184, s[36:37]
	global_store_short_d16_hi v188, v186, s[36:37] offset:64
	v_add_u32_e32 v188, 0x400, v188
	global_store_short v188, v185, s[36:37]
	global_store_short v188, v187, s[36:37] offset:64
	v_add_u32_e32 v188, 0x400, v188
	global_store_short_d16_hi v188, v185, s[36:37]
	global_store_short_d16_hi v188, v187, s[36:37] offset:64
	v_add_u32_e32 v188, 0x1400, v188
	s_waitcnt lgkmcnt(7)
	v_mul_f32_e32 v172, v120, v148
	v_mul_f32_e32 v173, v121, v149
	v_mul_f32_e32 v174, v122, v150
	v_mul_f32_e32 v175, v123, v151
	v_mul_f32_e32 v176, v56, v148
	v_mul_f32_e32 v177, v57, v149
	v_mul_f32_e32 v178, v58, v150
	v_mul_f32_e32 v179, v59, v151
	ds_read_b128 v[148:151], v138 offset:320
	v_cvt_pk_bf16_f32 v180, v172, v173
	v_cvt_pk_bf16_f32 v181, v174, v175
	v_cvt_pk_bf16_f32 v182, v176, v177
	v_cvt_pk_bf16_f32 v183, v178, v179
	global_store_short v188, v180, s[36:37]
	global_store_short v188, v182, s[36:37] offset:64
	v_add_u32_e32 v188, 0x400, v188
	global_store_short_d16_hi v188, v180, s[36:37]
	global_store_short_d16_hi v188, v182, s[36:37] offset:64
	v_add_u32_e32 v188, 0x400, v188
	global_store_short v188, v181, s[36:37]
	global_store_short v188, v183, s[36:37] offset:64
	v_add_u32_e32 v188, 0x400, v188
	global_store_short_d16_hi v188, v181, s[36:37]
	global_store_short_d16_hi v188, v183, s[36:37] offset:64
	v_add_u32_e32 v188, 0x1400, v188
	s_waitcnt lgkmcnt(7)
	v_mul_f32_e32 v172, v124, v152
	v_mul_f32_e32 v173, v125, v153
	v_mul_f32_e32 v174, v126, v154
	v_mul_f32_e32 v175, v127, v155
	v_mul_f32_e32 v176, v60, v152
	v_mul_f32_e32 v177, v61, v153
	v_mul_f32_e32 v178, v62, v154
	v_mul_f32_e32 v179, v63, v155
	ds_read_b128 v[152:155], v138 offset:352
	v_cvt_pk_bf16_f32 v184, v172, v173
	v_cvt_pk_bf16_f32 v185, v174, v175
	v_cvt_pk_bf16_f32 v186, v176, v177
	v_cvt_pk_bf16_f32 v187, v178, v179
	global_store_short v188, v184, s[36:37]
	global_store_short v188, v186, s[36:37] offset:64
	v_add_u32_e32 v188, 0x400, v188
	global_store_short_d16_hi v188, v184, s[36:37]
	global_store_short_d16_hi v188, v186, s[36:37] offset:64
	v_add_u32_e32 v188, 0x400, v188
	global_store_short v188, v185, s[36:37]
	global_store_short v188, v187, s[36:37] offset:64
	v_add_u32_e32 v188, 0x400, v188
	global_store_short_d16_hi v188, v185, s[36:37]
	global_store_short_d16_hi v188, v187, s[36:37] offset:64
	v_add_u32_e32 v188, 0x1400, v188
	s_waitcnt lgkmcnt(7)
	v_mul_f32_e32 v172, v80, v156
	v_mul_f32_e32 v173, v81, v157
	v_mul_f32_e32 v174, v82, v158
	v_mul_f32_e32 v175, v83, v159
	v_mul_f32_e32 v176, v0, v156
	v_mul_f32_e32 v177, v1, v157
	v_mul_f32_e32 v178, v2, v158
	v_mul_f32_e32 v179, v3, v159
	ds_read_b128 v[156:159], v138 offset:384
	v_cvt_pk_bf16_f32 v180, v172, v173
	v_cvt_pk_bf16_f32 v181, v174, v175
	v_cvt_pk_bf16_f32 v182, v176, v177
	v_cvt_pk_bf16_f32 v183, v178, v179
	global_store_short v188, v180, s[36:37]
	global_store_short v188, v182, s[36:37] offset:64
	v_add_u32_e32 v188, 0x400, v188
	global_store_short_d16_hi v188, v180, s[36:37]
	global_store_short_d16_hi v188, v182, s[36:37] offset:64
	v_add_u32_e32 v188, 0x400, v188
	global_store_short v188, v181, s[36:37]
	global_store_short v188, v183, s[36:37] offset:64
	v_add_u32_e32 v188, 0x400, v188
	global_store_short_d16_hi v188, v181, s[36:37]
	global_store_short_d16_hi v188, v183, s[36:37] offset:64
	v_add_u32_e32 v188, 0x1400, v188
	s_waitcnt lgkmcnt(7)
	v_mul_f32_e32 v172, v84, v160
	v_mul_f32_e32 v173, v85, v161
	v_mul_f32_e32 v174, v86, v162
	v_mul_f32_e32 v175, v87, v163
	v_mul_f32_e32 v176, v4, v160
	v_mul_f32_e32 v177, v5, v161
	v_mul_f32_e32 v178, v6, v162
	v_mul_f32_e32 v179, v7, v163
	ds_read_b128 v[160:163], v138 offset:416
	v_cvt_pk_bf16_f32 v184, v172, v173
	v_cvt_pk_bf16_f32 v185, v174, v175
	v_cvt_pk_bf16_f32 v186, v176, v177
	v_cvt_pk_bf16_f32 v187, v178, v179
	global_store_short v188, v184, s[36:37]
	global_store_short v188, v186, s[36:37] offset:64
	v_add_u32_e32 v188, 0x400, v188
	global_store_short_d16_hi v188, v184, s[36:37]
	global_store_short_d16_hi v188, v186, s[36:37] offset:64
	v_add_u32_e32 v188, 0x400, v188
	global_store_short v188, v185, s[36:37]
	global_store_short v188, v187, s[36:37] offset:64
	v_add_u32_e32 v188, 0x400, v188
	global_store_short_d16_hi v188, v185, s[36:37]
	global_store_short_d16_hi v188, v187, s[36:37] offset:64
	v_add_u32_e32 v188, 0x1400, v188
	s_waitcnt lgkmcnt(7)
	v_mul_f32_e32 v172, v88, v164
	v_mul_f32_e32 v173, v89, v165
	v_mul_f32_e32 v174, v90, v166
	v_mul_f32_e32 v175, v91, v167
	v_mul_f32_e32 v176, v8, v164
	v_mul_f32_e32 v177, v9, v165
	v_mul_f32_e32 v178, v10, v166
	v_mul_f32_e32 v179, v11, v167
	ds_read_b128 v[164:167], v138 offset:448
	v_cvt_pk_bf16_f32 v180, v172, v173
	v_cvt_pk_bf16_f32 v181, v174, v175
	v_cvt_pk_bf16_f32 v182, v176, v177
	v_cvt_pk_bf16_f32 v183, v178, v179
	global_store_short v188, v180, s[36:37]
	global_store_short v188, v182, s[36:37] offset:64
	v_add_u32_e32 v188, 0x400, v188
	global_store_short_d16_hi v188, v180, s[36:37]
	global_store_short_d16_hi v188, v182, s[36:37] offset:64
	v_add_u32_e32 v188, 0x400, v188
	global_store_short v188, v181, s[36:37]
	global_store_short v188, v183, s[36:37] offset:64
	v_add_u32_e32 v188, 0x400, v188
	global_store_short_d16_hi v188, v181, s[36:37]
	global_store_short_d16_hi v188, v183, s[36:37] offset:64
	v_add_u32_e32 v188, 0x1400, v188
	s_waitcnt lgkmcnt(7)
	v_mul_f32_e32 v172, v92, v168
	v_mul_f32_e32 v173, v93, v169
	v_mul_f32_e32 v174, v94, v170
	v_mul_f32_e32 v175, v95, v171
	v_mul_f32_e32 v176, v12, v168
	v_mul_f32_e32 v177, v13, v169
	v_mul_f32_e32 v178, v14, v170
	v_mul_f32_e32 v179, v15, v171
	ds_read_b128 v[168:171], v138 offset:480
	v_cvt_pk_bf16_f32 v184, v172, v173
	v_cvt_pk_bf16_f32 v185, v174, v175
	v_cvt_pk_bf16_f32 v186, v176, v177
	v_cvt_pk_bf16_f32 v187, v178, v179
	global_store_short v188, v184, s[36:37]
	global_store_short v188, v186, s[36:37] offset:64
	v_add_u32_e32 v188, 0x400, v188
	global_store_short_d16_hi v188, v184, s[36:37]
	global_store_short_d16_hi v188, v186, s[36:37] offset:64
	v_add_u32_e32 v188, 0x400, v188
	global_store_short v188, v185, s[36:37]
	global_store_short v188, v187, s[36:37] offset:64
	v_add_u32_e32 v188, 0x400, v188
	global_store_short_d16_hi v188, v185, s[36:37]
	global_store_short_d16_hi v188, v187, s[36:37] offset:64
	v_add_u32_e32 v188, 0x1400, v188
	s_waitcnt lgkmcnt(7)
	v_mul_f32_e32 v172, v96, v140
	v_mul_f32_e32 v173, v97, v141
	v_mul_f32_e32 v174, v98, v142
	v_mul_f32_e32 v175, v99, v143
	v_mul_f32_e32 v176, v32, v140
	v_mul_f32_e32 v177, v33, v141
	v_mul_f32_e32 v178, v34, v142
	v_mul_f32_e32 v179, v35, v143
	v_cvt_pk_bf16_f32 v180, v172, v173
	v_cvt_pk_bf16_f32 v181, v174, v175
	v_cvt_pk_bf16_f32 v182, v176, v177
	v_cvt_pk_bf16_f32 v183, v178, v179
	global_store_short v188, v180, s[36:37]
	global_store_short v188, v182, s[36:37] offset:64
	v_add_u32_e32 v188, 0x400, v188
	global_store_short_d16_hi v188, v180, s[36:37]
	global_store_short_d16_hi v188, v182, s[36:37] offset:64
	v_add_u32_e32 v188, 0x400, v188
	global_store_short v188, v181, s[36:37]
	global_store_short v188, v183, s[36:37] offset:64
	v_add_u32_e32 v188, 0x400, v188
	global_store_short_d16_hi v188, v181, s[36:37]
	global_store_short_d16_hi v188, v183, s[36:37] offset:64
	v_add_u32_e32 v188, 0x1400, v188
	s_waitcnt lgkmcnt(6)
	v_mul_f32_e32 v172, v100, v144
	v_mul_f32_e32 v173, v101, v145
	v_mul_f32_e32 v174, v102, v146
	v_mul_f32_e32 v175, v103, v147
	v_mul_f32_e32 v176, v36, v144
	v_mul_f32_e32 v177, v37, v145
	v_mul_f32_e32 v178, v38, v146
	v_mul_f32_e32 v179, v39, v147
	v_cvt_pk_bf16_f32 v184, v172, v173
	v_cvt_pk_bf16_f32 v185, v174, v175
	v_cvt_pk_bf16_f32 v186, v176, v177
	v_cvt_pk_bf16_f32 v187, v178, v179
	global_store_short v188, v184, s[36:37]
	global_store_short v188, v186, s[36:37] offset:64
	v_add_u32_e32 v188, 0x400, v188
	global_store_short_d16_hi v188, v184, s[36:37]
	global_store_short_d16_hi v188, v186, s[36:37] offset:64
	v_add_u32_e32 v188, 0x400, v188
	global_store_short v188, v185, s[36:37]
	global_store_short v188, v187, s[36:37] offset:64
	v_add_u32_e32 v188, 0x400, v188
	global_store_short_d16_hi v188, v185, s[36:37]
	global_store_short_d16_hi v188, v187, s[36:37] offset:64
	v_add_u32_e32 v188, 0x1400, v188
	s_waitcnt lgkmcnt(5)
	v_mul_f32_e32 v172, v104, v148
	v_mul_f32_e32 v173, v105, v149
	v_mul_f32_e32 v174, v106, v150
	v_mul_f32_e32 v175, v107, v151
	v_mul_f32_e32 v176, v40, v148
	v_mul_f32_e32 v177, v41, v149
	v_mul_f32_e32 v178, v42, v150
	v_mul_f32_e32 v179, v43, v151
	v_cvt_pk_bf16_f32 v180, v172, v173
	v_cvt_pk_bf16_f32 v181, v174, v175
	v_cvt_pk_bf16_f32 v182, v176, v177
	v_cvt_pk_bf16_f32 v183, v178, v179
	global_store_short v188, v180, s[36:37]
	global_store_short v188, v182, s[36:37] offset:64
	v_add_u32_e32 v188, 0x400, v188
	global_store_short_d16_hi v188, v180, s[36:37]
	global_store_short_d16_hi v188, v182, s[36:37] offset:64
	v_add_u32_e32 v188, 0x400, v188
	global_store_short v188, v181, s[36:37]
	global_store_short v188, v183, s[36:37] offset:64
	v_add_u32_e32 v188, 0x400, v188
	global_store_short_d16_hi v188, v181, s[36:37]
	global_store_short_d16_hi v188, v183, s[36:37] offset:64
	v_add_u32_e32 v188, 0x1400, v188
	s_waitcnt lgkmcnt(4)
	v_mul_f32_e32 v172, v108, v152
	v_mul_f32_e32 v173, v109, v153
	v_mul_f32_e32 v174, v110, v154
	v_mul_f32_e32 v175, v111, v155
	v_mul_f32_e32 v176, v44, v152
	v_mul_f32_e32 v177, v45, v153
	v_mul_f32_e32 v178, v46, v154
	v_mul_f32_e32 v179, v47, v155
	v_cvt_pk_bf16_f32 v184, v172, v173
	v_cvt_pk_bf16_f32 v185, v174, v175
	v_cvt_pk_bf16_f32 v186, v176, v177
	v_cvt_pk_bf16_f32 v187, v178, v179
	global_store_short v188, v184, s[36:37]
	global_store_short v188, v186, s[36:37] offset:64
	v_add_u32_e32 v188, 0x400, v188
	global_store_short_d16_hi v188, v184, s[36:37]
	global_store_short_d16_hi v188, v186, s[36:37] offset:64
	v_add_u32_e32 v188, 0x400, v188
	global_store_short v188, v185, s[36:37]
	global_store_short v188, v187, s[36:37] offset:64
	v_add_u32_e32 v188, 0x400, v188
	global_store_short_d16_hi v188, v185, s[36:37]
	global_store_short_d16_hi v188, v187, s[36:37] offset:64
	v_add_u32_e32 v188, 0x1400, v188
	s_waitcnt lgkmcnt(3)
	v_mul_f32_e32 v172, v64, v156
	v_mul_f32_e32 v173, v65, v157
	v_mul_f32_e32 v174, v66, v158
	v_mul_f32_e32 v175, v67, v159
	v_mul_f32_e32 v176, v16, v156
	v_mul_f32_e32 v177, v17, v157
	v_mul_f32_e32 v178, v18, v158
	v_mul_f32_e32 v179, v19, v159
	v_cvt_pk_bf16_f32 v180, v172, v173
	v_cvt_pk_bf16_f32 v181, v174, v175
	v_cvt_pk_bf16_f32 v182, v176, v177
	v_cvt_pk_bf16_f32 v183, v178, v179
	global_store_short v188, v180, s[36:37]
	global_store_short v188, v182, s[36:37] offset:64
	v_add_u32_e32 v188, 0x400, v188
	global_store_short_d16_hi v188, v180, s[36:37]
	global_store_short_d16_hi v188, v182, s[36:37] offset:64
	v_add_u32_e32 v188, 0x400, v188
	global_store_short v188, v181, s[36:37]
	global_store_short v188, v183, s[36:37] offset:64
	v_add_u32_e32 v188, 0x400, v188
	global_store_short_d16_hi v188, v181, s[36:37]
	global_store_short_d16_hi v188, v183, s[36:37] offset:64
	v_add_u32_e32 v188, 0x1400, v188
	s_waitcnt lgkmcnt(2)
	v_mul_f32_e32 v172, v68, v160
	v_mul_f32_e32 v173, v69, v161
	v_mul_f32_e32 v174, v70, v162
	v_mul_f32_e32 v175, v71, v163
	v_mul_f32_e32 v176, v20, v160
	v_mul_f32_e32 v177, v21, v161
	v_mul_f32_e32 v178, v22, v162
	v_mul_f32_e32 v179, v23, v163
	v_cvt_pk_bf16_f32 v184, v172, v173
	v_cvt_pk_bf16_f32 v185, v174, v175
	v_cvt_pk_bf16_f32 v186, v176, v177
	v_cvt_pk_bf16_f32 v187, v178, v179
	global_store_short v188, v184, s[36:37]
	global_store_short v188, v186, s[36:37] offset:64
	v_add_u32_e32 v188, 0x400, v188
	global_store_short_d16_hi v188, v184, s[36:37]
	global_store_short_d16_hi v188, v186, s[36:37] offset:64
	v_add_u32_e32 v188, 0x400, v188
	global_store_short v188, v185, s[36:37]
	global_store_short v188, v187, s[36:37] offset:64
	v_add_u32_e32 v188, 0x400, v188
	global_store_short_d16_hi v188, v185, s[36:37]
	global_store_short_d16_hi v188, v187, s[36:37] offset:64
	v_add_u32_e32 v188, 0x1400, v188
	s_waitcnt lgkmcnt(1)
	v_mul_f32_e32 v172, v72, v164
	v_mul_f32_e32 v173, v73, v165
	v_mul_f32_e32 v174, v74, v166
	v_mul_f32_e32 v175, v75, v167
	v_mul_f32_e32 v176, v24, v164
	v_mul_f32_e32 v177, v25, v165
	v_mul_f32_e32 v178, v26, v166
	v_mul_f32_e32 v179, v27, v167
	v_cvt_pk_bf16_f32 v180, v172, v173
	v_cvt_pk_bf16_f32 v181, v174, v175
	v_cvt_pk_bf16_f32 v182, v176, v177
	v_cvt_pk_bf16_f32 v183, v178, v179
	global_store_short v188, v180, s[36:37]
	global_store_short v188, v182, s[36:37] offset:64
	v_add_u32_e32 v188, 0x400, v188
	global_store_short_d16_hi v188, v180, s[36:37]
	global_store_short_d16_hi v188, v182, s[36:37] offset:64
	v_add_u32_e32 v188, 0x400, v188
	global_store_short v188, v181, s[36:37]
	global_store_short v188, v183, s[36:37] offset:64
	v_add_u32_e32 v188, 0x400, v188
	global_store_short_d16_hi v188, v181, s[36:37]
	global_store_short_d16_hi v188, v183, s[36:37] offset:64
	v_add_u32_e32 v188, 0x1400, v188
	s_waitcnt lgkmcnt(0)
	v_mul_f32_e32 v172, v76, v168
	v_mul_f32_e32 v173, v77, v169
	v_mul_f32_e32 v174, v78, v170
	v_mul_f32_e32 v175, v79, v171
	v_mul_f32_e32 v176, v28, v168
	v_mul_f32_e32 v177, v29, v169
	v_mul_f32_e32 v178, v30, v170
	v_mul_f32_e32 v179, v31, v171
	v_cvt_pk_bf16_f32 v184, v172, v173
	v_cvt_pk_bf16_f32 v185, v174, v175
	v_cvt_pk_bf16_f32 v186, v176, v177
	v_cvt_pk_bf16_f32 v187, v178, v179
	global_store_short v188, v184, s[36:37]
	global_store_short v188, v186, s[36:37] offset:64
	v_add_u32_e32 v188, 0x400, v188
	global_store_short_d16_hi v188, v184, s[36:37]
	global_store_short_d16_hi v188, v186, s[36:37] offset:64
	v_add_u32_e32 v188, 0x400, v188
	global_store_short v188, v185, s[36:37]
	global_store_short v188, v187, s[36:37] offset:64
	v_add_u32_e32 v188, 0x400, v188
	global_store_short_d16_hi v188, v185, s[36:37]
	global_store_short_d16_hi v188, v187, s[36:37] offset:64
	s_branch .LBB0_3056
